# phase_tail gate: f32 MFMA groups interleaved with the logsigmoid VALU blocks (matrix pipe runs in the shadow of VALU issue; MFMA->VALU s_nop padding removed)
# speedup vs baseline: 1.0102x; 1.0027x over previous
.Ltail_gate:
	v_and_b32_e32 v53, 15, v0
	v_bfe_u32 v54, v0, 4, 2
	v_lshrrev_b32_e32 v55, 8, v0
	v_mul_u32_u24_e32 v40, 0x90, v53
	v_lshl_add_u32 v40, v54, 2, v40
	v_lshl_add_u32 v40, v55, 6, v40
	v_add_u32_e32 v40, 0xc600, v40
	ds_read_b32 v41, v40
	ds_read_b32 v42, v40 offset:16
	ds_read_b32 v43, v40 offset:32
	ds_read_b32 v44, v40 offset:48
	ds_read_b32 v45, v40 offset:2304
	ds_read_b32 v46, v40 offset:2320
	ds_read_b32 v47, v40 offset:2336
	ds_read_b32 v48, v40 offset:2352
	ds_read_b32 v49, v40 offset:4608
	ds_read_b32 v50, v40 offset:4624
	ds_read_b32 v51, v40 offset:4640
	ds_read_b32 v52, v40 offset:4656
	s_ashr_i32 s5, s10, 31
	s_mov_b32 s4, s10
	s_lshl_b64 s[4:5], s[4:5], 10
	s_add_u32 s4, s4, s24
	s_addc_u32 s5, s5, s25
	s_add_u32 s4, s4, 0x7522000
	s_addc_u32 s5, s5, 0
	v_lshrrev_b32_e32 v55, 6, v0
	v_lshlrev_b32_e32 v56, 12, v54
	v_lshl_add_u32 v56, v55, 7, v56
	v_lshl_add_u32 v56, v53, 3, v56
	v_mov_b32_e32 v57, 0
	v_lshl_add_u64 v[168:169], s[4:5], 0, v[56:57]
	s_mov_b64 s[6:7], 0x4000
	v_lshl_add_u64 v[170:171], v[168:169], 0, s[6:7]
	v_lshl_add_u64 v[172:173], v[170:171], 0, s[6:7]
	s_waitcnt vmcnt(0) lgkmcnt(0)
	v_mfma_f32_16x16x4_f32 v[120:123], v41, v100, 0
	v_mfma_f32_16x16x4_f32 v[124:127], v41, v101, 0
	v_mfma_f32_16x16x4_f32 v[128:131], v41, v102, 0
	v_mfma_f32_16x16x4_f32 v[132:135], v41, v103, 0
	v_mfma_f32_16x16x4_f32 v[120:123], v42, v104, v[120:123]
	v_mfma_f32_16x16x4_f32 v[124:127], v42, v105, v[124:127]
	v_mfma_f32_16x16x4_f32 v[128:131], v42, v106, v[128:131]
	v_mfma_f32_16x16x4_f32 v[132:135], v42, v107, v[132:135]
	v_mfma_f32_16x16x4_f32 v[120:123], v43, v108, v[120:123]
	v_mfma_f32_16x16x4_f32 v[124:127], v43, v109, v[124:127]
	v_mfma_f32_16x16x4_f32 v[128:131], v43, v110, v[128:131]
	v_mfma_f32_16x16x4_f32 v[132:135], v43, v111, v[132:135]
	v_mfma_f32_16x16x4_f32 v[120:123], v44, v112, v[120:123]
	v_mfma_f32_16x16x4_f32 v[124:127], v44, v113, v[124:127]
	v_mfma_f32_16x16x4_f32 v[128:131], v44, v114, v[128:131]
	v_mfma_f32_16x16x4_f32 v[132:135], v44, v115, v[132:135]
	v_mfma_f32_16x16x4_f32 v[136:139], v45, v100, 0
	v_mfma_f32_16x16x4_f32 v[140:143], v45, v101, 0
	v_mfma_f32_16x16x4_f32 v[144:147], v45, v102, 0
	v_mfma_f32_16x16x4_f32 v[148:151], v45, v103, 0
	v_mfma_f32_16x16x4_f32 v[136:139], v46, v104, v[136:139]
	v_mfma_f32_16x16x4_f32 v[140:143], v46, v105, v[140:143]
	v_mfma_f32_16x16x4_f32 v[144:147], v46, v106, v[144:147]
	v_mfma_f32_16x16x4_f32 v[148:151], v46, v107, v[148:151]
	v_mfma_f32_16x16x4_f32 v[136:139], v47, v108, v[136:139]
	v_mfma_f32_16x16x4_f32 v[140:143], v47, v109, v[140:143]
	v_mfma_f32_16x16x4_f32 v[144:147], v47, v110, v[144:147]
	v_mfma_f32_16x16x4_f32 v[148:151], v47, v111, v[148:151]
	v_mfma_f32_16x16x4_f32 v[136:139], v48, v112, v[136:139]
	v_mfma_f32_16x16x4_f32 v[140:143], v48, v113, v[140:143]
	v_mfma_f32_16x16x4_f32 v[144:147], v48, v114, v[144:147]
	v_mfma_f32_16x16x4_f32 v[148:151], v48, v115, v[148:151]
	v_add_f32_e32 v120, v116, v120
	v_add_f32_e32 v124, v117, v124
	v_add_f32_e32 v128, v118, v128
	v_add_f32_e32 v132, v119, v132
	v_add_f32_e32 v121, v116, v121
	v_add_f32_e32 v125, v117, v125
	v_add_f32_e32 v129, v118, v129
	v_add_f32_e32 v133, v119, v133
	v_add_f32_e32 v122, v116, v122
	v_add_f32_e32 v126, v117, v126
	v_add_f32_e32 v130, v118, v130
	v_add_f32_e32 v134, v119, v134
	v_add_f32_e32 v123, v116, v123
	v_add_f32_e32 v127, v117, v127
	v_add_f32_e32 v131, v118, v131
	v_add_f32_e32 v135, v119, v135
	v_min_f32_e32 v53, 0, v120
	v_min_f32_e32 v54, 0, v124
	v_min_f32_e32 v55, 0, v128
	v_min_f32_e32 v56, 0, v132
	v_min_f32_e32 v57, 0, v121
	v_min_f32_e32 v58, 0, v125
	v_min_f32_e32 v59, 0, v129
	v_min_f32_e32 v60, 0, v133
	v_min_f32_e32 v61, 0, v122
	v_min_f32_e32 v62, 0, v126
	v_min_f32_e32 v63, 0, v130
	v_min_f32_e32 v64, 0, v134
	v_min_f32_e32 v65, 0, v123
	v_min_f32_e32 v66, 0, v127
	v_min_f32_e32 v67, 0, v131
	v_min_f32_e32 v68, 0, v135
	v_mul_f32_e64 v120, |v120|, s13
	v_mul_f32_e64 v124, |v124|, s13
	v_mul_f32_e64 v128, |v128|, s13
	v_mul_f32_e64 v132, |v132|, s13
	v_mul_f32_e64 v121, |v121|, s13
	v_mul_f32_e64 v125, |v125|, s13
	v_mul_f32_e64 v129, |v129|, s13
	v_mul_f32_e64 v133, |v133|, s13
	v_mul_f32_e64 v122, |v122|, s13
	v_mul_f32_e64 v126, |v126|, s13
	v_mul_f32_e64 v130, |v130|, s13
	v_mul_f32_e64 v134, |v134|, s13
	v_mul_f32_e64 v123, |v123|, s13
	v_mul_f32_e64 v127, |v127|, s13
	v_mul_f32_e64 v131, |v131|, s13
	v_mul_f32_e64 v135, |v135|, s13
	v_exp_f32_e32 v120, v120
	v_exp_f32_e32 v124, v124
	v_exp_f32_e32 v128, v128
	v_exp_f32_e32 v132, v132
	v_exp_f32_e32 v121, v121
	v_exp_f32_e32 v125, v125
	v_exp_f32_e32 v129, v129
	v_exp_f32_e32 v133, v133
	v_exp_f32_e32 v122, v122
	v_exp_f32_e32 v126, v126
	v_exp_f32_e32 v130, v130
	v_exp_f32_e32 v134, v134
	v_exp_f32_e32 v123, v123
	v_exp_f32_e32 v127, v127
	v_exp_f32_e32 v131, v131
	v_exp_f32_e32 v135, v135
	v_add_f32_e32 v120, 1.0, v120
	v_add_f32_e32 v124, 1.0, v124
	v_add_f32_e32 v128, 1.0, v128
	v_add_f32_e32 v132, 1.0, v132
	v_add_f32_e32 v121, 1.0, v121
	v_add_f32_e32 v125, 1.0, v125
	v_add_f32_e32 v129, 1.0, v129
	v_add_f32_e32 v133, 1.0, v133
	v_add_f32_e32 v122, 1.0, v122
	v_add_f32_e32 v126, 1.0, v126
	v_add_f32_e32 v130, 1.0, v130
	v_add_f32_e32 v134, 1.0, v134
	v_add_f32_e32 v123, 1.0, v123
	v_add_f32_e32 v127, 1.0, v127
	v_add_f32_e32 v131, 1.0, v131
	v_add_f32_e32 v135, 1.0, v135
	v_log_f32_e32 v120, v120
	v_log_f32_e32 v124, v124
	v_log_f32_e32 v128, v128
	v_log_f32_e32 v132, v132
	v_log_f32_e32 v121, v121
	v_log_f32_e32 v125, v125
	v_log_f32_e32 v129, v129
	v_log_f32_e32 v133, v133
	v_log_f32_e32 v122, v122
	v_log_f32_e32 v126, v126
	v_log_f32_e32 v130, v130
	v_log_f32_e32 v134, v134
	v_log_f32_e32 v123, v123
	v_log_f32_e32 v127, v127
	v_log_f32_e32 v131, v131
	v_log_f32_e32 v135, v135
	v_mul_f32_e32 v69, 0x3f317217, v120
	v_mul_f32_e32 v70, 0x3f317217, v124
	v_mul_f32_e32 v71, 0x3f317217, v128
	v_mul_f32_e32 v72, 0x3f317217, v132
	v_mul_f32_e32 v73, 0x3f317217, v121
	v_mul_f32_e32 v74, 0x3f317217, v125
	v_mul_f32_e32 v75, 0x3f317217, v129
	v_mul_f32_e32 v76, 0x3f317217, v133
	v_mul_f32_e32 v77, 0x3f317217, v122
	v_mul_f32_e32 v78, 0x3f317217, v126
	v_mul_f32_e32 v79, 0x3f317217, v130
	v_mul_f32_e32 v80, 0x3f317217, v134
	v_mul_f32_e32 v81, 0x3f317217, v123
	v_mul_f32_e32 v82, 0x3f317217, v127
	v_mul_f32_e32 v83, 0x3f317217, v131
	v_mul_f32_e32 v84, 0x3f317217, v135
	v_fma_f32 v69, v120, s15, -v69
	v_fma_f32 v70, v124, s15, -v70
	v_fma_f32 v71, v128, s15, -v71
	v_fma_f32 v72, v132, s15, -v72
	v_fma_f32 v73, v121, s15, -v73
	v_fma_f32 v74, v125, s15, -v74
	v_fma_f32 v75, v129, s15, -v75
	v_fma_f32 v76, v133, s15, -v76
	v_fma_f32 v77, v122, s15, -v77
	v_fma_f32 v78, v126, s15, -v78
	v_fma_f32 v79, v130, s15, -v79
	v_fma_f32 v80, v134, s15, -v80
	v_fma_f32 v81, v123, s15, -v81
	v_fma_f32 v82, v127, s15, -v82
	v_fma_f32 v83, v131, s15, -v83
	v_fma_f32 v84, v135, s15, -v84
	v_fmac_f32_e32 v69, 0x3377d1cf, v120
	v_fmac_f32_e32 v70, 0x3377d1cf, v124
	v_fmac_f32_e32 v71, 0x3377d1cf, v128
	v_fmac_f32_e32 v72, 0x3377d1cf, v132
	v_fmac_f32_e32 v73, 0x3377d1cf, v121
	v_fmac_f32_e32 v74, 0x3377d1cf, v125
	v_fmac_f32_e32 v75, 0x3377d1cf, v129
	v_fmac_f32_e32 v76, 0x3377d1cf, v133
	v_fmac_f32_e32 v77, 0x3377d1cf, v122
	v_fmac_f32_e32 v78, 0x3377d1cf, v126
	v_fmac_f32_e32 v79, 0x3377d1cf, v130
	v_fmac_f32_e32 v80, 0x3377d1cf, v134
	v_fmac_f32_e32 v81, 0x3377d1cf, v123
	v_fmac_f32_e32 v82, 0x3377d1cf, v127
	v_fmac_f32_e32 v83, 0x3377d1cf, v131
	v_fmac_f32_e32 v84, 0x3377d1cf, v135
	v_fmac_f32_e32 v69, 0x3f317217, v120
	v_fmac_f32_e32 v70, 0x3f317217, v124
	v_fmac_f32_e32 v71, 0x3f317217, v128
	v_fmac_f32_e32 v72, 0x3f317217, v132
	v_fmac_f32_e32 v73, 0x3f317217, v121
	v_fmac_f32_e32 v74, 0x3f317217, v125
	v_fmac_f32_e32 v75, 0x3f317217, v129
	v_fmac_f32_e32 v76, 0x3f317217, v133
	v_fmac_f32_e32 v77, 0x3f317217, v122
	v_fmac_f32_e32 v78, 0x3f317217, v126
	v_fmac_f32_e32 v79, 0x3f317217, v130
	v_fmac_f32_e32 v80, 0x3f317217, v134
	v_fmac_f32_e32 v81, 0x3f317217, v123
	v_fmac_f32_e32 v82, 0x3f317217, v127
	v_fmac_f32_e32 v83, 0x3f317217, v131
	v_fmac_f32_e32 v84, 0x3f317217, v135
	v_sub_f32_e32 v120, v53, v69
	v_sub_f32_e32 v124, v54, v70
	v_sub_f32_e32 v128, v55, v71
	v_sub_f32_e32 v132, v56, v72
	v_sub_f32_e32 v121, v57, v73
	v_sub_f32_e32 v125, v58, v74
	v_sub_f32_e32 v129, v59, v75
	v_sub_f32_e32 v133, v60, v76
	v_sub_f32_e32 v122, v61, v77
	v_sub_f32_e32 v126, v62, v78
	v_sub_f32_e32 v130, v63, v79
	v_sub_f32_e32 v134, v64, v80
	v_sub_f32_e32 v123, v65, v81
	v_sub_f32_e32 v127, v66, v82
	v_sub_f32_e32 v131, v67, v83
	v_sub_f32_e32 v135, v68, v84
	v_fma_mixlo_f16 v86, v120, s17, 0
	v_fma_mixlo_f16 v87, v128, s17, 0
	v_fma_mixlo_f16 v88, v121, s17, 0
	v_fma_mixlo_f16 v89, v129, s17, 0
	v_fma_mixlo_f16 v90, v122, s17, 0
	v_fma_mixlo_f16 v91, v130, s17, 0
	v_fma_mixlo_f16 v92, v123, s17, 0
	v_fma_mixlo_f16 v93, v131, s17, 0
	v_fma_mixhi_f16 v86, v124, s17, 0
	v_fma_mixhi_f16 v87, v132, s17, 0
	v_fma_mixhi_f16 v88, v125, s17, 0
	v_fma_mixhi_f16 v89, v133, s17, 0
	v_fma_mixhi_f16 v90, v126, s17, 0
	v_fma_mixhi_f16 v91, v134, s17, 0
	v_fma_mixhi_f16 v92, v127, s17, 0
	v_fma_mixhi_f16 v93, v135, s17, 0
	global_store_dwordx2 v[168:169], v[86:87], off
	global_store_dwordx2 v[168:169], v[88:89], off offset:1024
	global_store_dwordx2 v[168:169], v[90:91], off offset:2048
	global_store_dwordx2 v[168:169], v[92:93], off offset:3072
	v_mfma_f32_16x16x4_f32 v[152:155], v49, v100, 0
	v_mfma_f32_16x16x4_f32 v[156:159], v49, v101, 0
	v_mfma_f32_16x16x4_f32 v[160:163], v49, v102, 0
	v_mfma_f32_16x16x4_f32 v[164:167], v49, v103, 0
	v_mfma_f32_16x16x4_f32 v[152:155], v50, v104, v[152:155]
	v_mfma_f32_16x16x4_f32 v[156:159], v50, v105, v[156:159]
	v_mfma_f32_16x16x4_f32 v[160:163], v50, v106, v[160:163]
	v_mfma_f32_16x16x4_f32 v[164:167], v50, v107, v[164:167]
	v_mfma_f32_16x16x4_f32 v[152:155], v51, v108, v[152:155]
	v_mfma_f32_16x16x4_f32 v[156:159], v51, v109, v[156:159]
	v_mfma_f32_16x16x4_f32 v[160:163], v51, v110, v[160:163]
	v_mfma_f32_16x16x4_f32 v[164:167], v51, v111, v[164:167]
	v_mfma_f32_16x16x4_f32 v[152:155], v52, v112, v[152:155]
	v_mfma_f32_16x16x4_f32 v[156:159], v52, v113, v[156:159]
	v_mfma_f32_16x16x4_f32 v[160:163], v52, v114, v[160:163]
	v_mfma_f32_16x16x4_f32 v[164:167], v52, v115, v[164:167]
	v_add_f32_e32 v136, v116, v136
	v_add_f32_e32 v140, v117, v140
	v_add_f32_e32 v144, v118, v144
	v_add_f32_e32 v148, v119, v148
	v_add_f32_e32 v137, v116, v137
	v_add_f32_e32 v141, v117, v141
	v_add_f32_e32 v145, v118, v145
	v_add_f32_e32 v149, v119, v149
	v_add_f32_e32 v138, v116, v138
	v_add_f32_e32 v142, v117, v142
	v_add_f32_e32 v146, v118, v146
	v_add_f32_e32 v150, v119, v150
	v_add_f32_e32 v139, v116, v139
	v_add_f32_e32 v143, v117, v143
	v_add_f32_e32 v147, v118, v147
	v_add_f32_e32 v151, v119, v151
	v_min_f32_e32 v53, 0, v136
	v_min_f32_e32 v54, 0, v140
	v_min_f32_e32 v55, 0, v144
	v_min_f32_e32 v56, 0, v148
	v_min_f32_e32 v57, 0, v137
	v_min_f32_e32 v58, 0, v141
	v_min_f32_e32 v59, 0, v145
	v_min_f32_e32 v60, 0, v149
	v_min_f32_e32 v61, 0, v138
	v_min_f32_e32 v62, 0, v142
	v_min_f32_e32 v63, 0, v146
	v_min_f32_e32 v64, 0, v150
	v_min_f32_e32 v65, 0, v139
	v_min_f32_e32 v66, 0, v143
	v_min_f32_e32 v67, 0, v147
	v_min_f32_e32 v68, 0, v151
	v_mul_f32_e64 v136, |v136|, s13
	v_mul_f32_e64 v140, |v140|, s13
	v_mul_f32_e64 v144, |v144|, s13
	v_mul_f32_e64 v148, |v148|, s13
	v_mul_f32_e64 v137, |v137|, s13
	v_mul_f32_e64 v141, |v141|, s13
	v_mul_f32_e64 v145, |v145|, s13
	v_mul_f32_e64 v149, |v149|, s13
	v_mul_f32_e64 v138, |v138|, s13
	v_mul_f32_e64 v142, |v142|, s13
	v_mul_f32_e64 v146, |v146|, s13
	v_mul_f32_e64 v150, |v150|, s13
	v_mul_f32_e64 v139, |v139|, s13
	v_mul_f32_e64 v143, |v143|, s13
	v_mul_f32_e64 v147, |v147|, s13
	v_mul_f32_e64 v151, |v151|, s13
	v_exp_f32_e32 v136, v136
	v_exp_f32_e32 v140, v140
	v_exp_f32_e32 v144, v144
	v_exp_f32_e32 v148, v148
	v_exp_f32_e32 v137, v137
	v_exp_f32_e32 v141, v141
	v_exp_f32_e32 v145, v145
	v_exp_f32_e32 v149, v149
	v_exp_f32_e32 v138, v138
	v_exp_f32_e32 v142, v142
	v_exp_f32_e32 v146, v146
	v_exp_f32_e32 v150, v150
	v_exp_f32_e32 v139, v139
	v_exp_f32_e32 v143, v143
	v_exp_f32_e32 v147, v147
	v_exp_f32_e32 v151, v151
	v_add_f32_e32 v136, 1.0, v136
	v_add_f32_e32 v140, 1.0, v140
	v_add_f32_e32 v144, 1.0, v144
	v_add_f32_e32 v148, 1.0, v148
	v_add_f32_e32 v137, 1.0, v137
	v_add_f32_e32 v141, 1.0, v141
	v_add_f32_e32 v145, 1.0, v145
	v_add_f32_e32 v149, 1.0, v149
	v_add_f32_e32 v138, 1.0, v138
	v_add_f32_e32 v142, 1.0, v142
	v_add_f32_e32 v146, 1.0, v146
	v_add_f32_e32 v150, 1.0, v150
	v_add_f32_e32 v139, 1.0, v139
	v_add_f32_e32 v143, 1.0, v143
	v_add_f32_e32 v147, 1.0, v147
	v_add_f32_e32 v151, 1.0, v151
	v_log_f32_e32 v136, v136
	v_log_f32_e32 v140, v140
	v_log_f32_e32 v144, v144
	v_log_f32_e32 v148, v148
	v_log_f32_e32 v137, v137
	v_log_f32_e32 v141, v141
	v_log_f32_e32 v145, v145
	v_log_f32_e32 v149, v149
	v_log_f32_e32 v138, v138
	v_log_f32_e32 v142, v142
	v_log_f32_e32 v146, v146
	v_log_f32_e32 v150, v150
	v_log_f32_e32 v139, v139
	v_log_f32_e32 v143, v143
	v_log_f32_e32 v147, v147
	v_log_f32_e32 v151, v151
	v_mul_f32_e32 v69, 0x3f317217, v136
	v_mul_f32_e32 v70, 0x3f317217, v140
	v_mul_f32_e32 v71, 0x3f317217, v144
	v_mul_f32_e32 v72, 0x3f317217, v148
	v_mul_f32_e32 v73, 0x3f317217, v137
	v_mul_f32_e32 v74, 0x3f317217, v141
	v_mul_f32_e32 v75, 0x3f317217, v145
	v_mul_f32_e32 v76, 0x3f317217, v149
	v_mul_f32_e32 v77, 0x3f317217, v138
	v_mul_f32_e32 v78, 0x3f317217, v142
	v_mul_f32_e32 v79, 0x3f317217, v146
	v_mul_f32_e32 v80, 0x3f317217, v150
	v_mul_f32_e32 v81, 0x3f317217, v139
	v_mul_f32_e32 v82, 0x3f317217, v143
	v_mul_f32_e32 v83, 0x3f317217, v147
	v_mul_f32_e32 v84, 0x3f317217, v151
	v_fma_f32 v69, v136, s15, -v69
	v_fma_f32 v70, v140, s15, -v70
	v_fma_f32 v71, v144, s15, -v71
	v_fma_f32 v72, v148, s15, -v72
	v_fma_f32 v73, v137, s15, -v73
	v_fma_f32 v74, v141, s15, -v74
	v_fma_f32 v75, v145, s15, -v75
	v_fma_f32 v76, v149, s15, -v76
	v_fma_f32 v77, v138, s15, -v77
	v_fma_f32 v78, v142, s15, -v78
	v_fma_f32 v79, v146, s15, -v79
	v_fma_f32 v80, v150, s15, -v80
	v_fma_f32 v81, v139, s15, -v81
	v_fma_f32 v82, v143, s15, -v82
	v_fma_f32 v83, v147, s15, -v83
	v_fma_f32 v84, v151, s15, -v84
	v_fmac_f32_e32 v69, 0x3377d1cf, v136
	v_fmac_f32_e32 v70, 0x3377d1cf, v140
	v_fmac_f32_e32 v71, 0x3377d1cf, v144
	v_fmac_f32_e32 v72, 0x3377d1cf, v148
	v_fmac_f32_e32 v73, 0x3377d1cf, v137
	v_fmac_f32_e32 v74, 0x3377d1cf, v141
	v_fmac_f32_e32 v75, 0x3377d1cf, v145
	v_fmac_f32_e32 v76, 0x3377d1cf, v149
	v_fmac_f32_e32 v77, 0x3377d1cf, v138
	v_fmac_f32_e32 v78, 0x3377d1cf, v142
	v_fmac_f32_e32 v79, 0x3377d1cf, v146
	v_fmac_f32_e32 v80, 0x3377d1cf, v150
	v_fmac_f32_e32 v81, 0x3377d1cf, v139
	v_fmac_f32_e32 v82, 0x3377d1cf, v143
	v_fmac_f32_e32 v83, 0x3377d1cf, v147
	v_fmac_f32_e32 v84, 0x3377d1cf, v151
	v_fmac_f32_e32 v69, 0x3f317217, v136
	v_fmac_f32_e32 v70, 0x3f317217, v140
	v_fmac_f32_e32 v71, 0x3f317217, v144
	v_fmac_f32_e32 v72, 0x3f317217, v148
	v_fmac_f32_e32 v73, 0x3f317217, v137
	v_fmac_f32_e32 v74, 0x3f317217, v141
	v_fmac_f32_e32 v75, 0x3f317217, v145
	v_fmac_f32_e32 v76, 0x3f317217, v149
	v_fmac_f32_e32 v77, 0x3f317217, v138
	v_fmac_f32_e32 v78, 0x3f317217, v142
	v_fmac_f32_e32 v79, 0x3f317217, v146
	v_fmac_f32_e32 v80, 0x3f317217, v150
	v_fmac_f32_e32 v81, 0x3f317217, v139
	v_fmac_f32_e32 v82, 0x3f317217, v143
	v_fmac_f32_e32 v83, 0x3f317217, v147
	v_fmac_f32_e32 v84, 0x3f317217, v151
	v_sub_f32_e32 v136, v53, v69
	v_sub_f32_e32 v140, v54, v70
	v_sub_f32_e32 v144, v55, v71
	v_sub_f32_e32 v148, v56, v72
	v_sub_f32_e32 v137, v57, v73
	v_sub_f32_e32 v141, v58, v74
	v_sub_f32_e32 v145, v59, v75
	v_sub_f32_e32 v149, v60, v76
	v_sub_f32_e32 v138, v61, v77
	v_sub_f32_e32 v142, v62, v78
	v_sub_f32_e32 v146, v63, v79
	v_sub_f32_e32 v150, v64, v80
	v_sub_f32_e32 v139, v65, v81
	v_sub_f32_e32 v143, v66, v82
	v_sub_f32_e32 v147, v67, v83
	v_sub_f32_e32 v151, v68, v84
	v_fma_mixlo_f16 v86, v136, s17, 0
	v_fma_mixlo_f16 v87, v144, s17, 0
	v_fma_mixlo_f16 v88, v137, s17, 0
	v_fma_mixlo_f16 v89, v145, s17, 0
	v_fma_mixlo_f16 v90, v138, s17, 0
	v_fma_mixlo_f16 v91, v146, s17, 0
	v_fma_mixlo_f16 v92, v139, s17, 0
	v_fma_mixlo_f16 v93, v147, s17, 0
	v_fma_mixhi_f16 v86, v140, s17, 0
	v_fma_mixhi_f16 v87, v148, s17, 0
	v_fma_mixhi_f16 v88, v141, s17, 0
	v_fma_mixhi_f16 v89, v149, s17, 0
	v_fma_mixhi_f16 v90, v142, s17, 0
	v_fma_mixhi_f16 v91, v150, s17, 0
	v_fma_mixhi_f16 v92, v143, s17, 0
	v_fma_mixhi_f16 v93, v151, s17, 0
	global_store_dwordx2 v[170:171], v[86:87], off
	global_store_dwordx2 v[170:171], v[88:89], off offset:1024
	global_store_dwordx2 v[170:171], v[90:91], off offset:2048
	global_store_dwordx2 v[170:171], v[92:93], off offset:3072
	v_add_f32_e32 v152, v116, v152
	v_add_f32_e32 v156, v117, v156
	v_add_f32_e32 v160, v118, v160
	v_add_f32_e32 v164, v119, v164
	v_add_f32_e32 v153, v116, v153
	v_add_f32_e32 v157, v117, v157
	v_add_f32_e32 v161, v118, v161
	v_add_f32_e32 v165, v119, v165
	v_add_f32_e32 v154, v116, v154
	v_add_f32_e32 v158, v117, v158
	v_add_f32_e32 v162, v118, v162
	v_add_f32_e32 v166, v119, v166
	v_add_f32_e32 v155, v116, v155
	v_add_f32_e32 v159, v117, v159
	v_add_f32_e32 v163, v118, v163
	v_add_f32_e32 v167, v119, v167
	v_min_f32_e32 v53, 0, v152
	v_min_f32_e32 v54, 0, v156
	v_min_f32_e32 v55, 0, v160
	v_min_f32_e32 v56, 0, v164
	v_min_f32_e32 v57, 0, v153
	v_min_f32_e32 v58, 0, v157
	v_min_f32_e32 v59, 0, v161
	v_min_f32_e32 v60, 0, v165
	v_min_f32_e32 v61, 0, v154
	v_min_f32_e32 v62, 0, v158
	v_min_f32_e32 v63, 0, v162
	v_min_f32_e32 v64, 0, v166
	v_min_f32_e32 v65, 0, v155
	v_min_f32_e32 v66, 0, v159
	v_min_f32_e32 v67, 0, v163
	v_min_f32_e32 v68, 0, v167
	v_mul_f32_e64 v152, |v152|, s13
	v_mul_f32_e64 v156, |v156|, s13
	v_mul_f32_e64 v160, |v160|, s13
	v_mul_f32_e64 v164, |v164|, s13
	v_mul_f32_e64 v153, |v153|, s13
	v_mul_f32_e64 v157, |v157|, s13
	v_mul_f32_e64 v161, |v161|, s13
	v_mul_f32_e64 v165, |v165|, s13
	v_mul_f32_e64 v154, |v154|, s13
	v_mul_f32_e64 v158, |v158|, s13
	v_mul_f32_e64 v162, |v162|, s13
	v_mul_f32_e64 v166, |v166|, s13
	v_mul_f32_e64 v155, |v155|, s13
	v_mul_f32_e64 v159, |v159|, s13
	v_mul_f32_e64 v163, |v163|, s13
	v_mul_f32_e64 v167, |v167|, s13
	v_exp_f32_e32 v152, v152
	v_exp_f32_e32 v156, v156
	v_exp_f32_e32 v160, v160
	v_exp_f32_e32 v164, v164
	v_exp_f32_e32 v153, v153
	v_exp_f32_e32 v157, v157
	v_exp_f32_e32 v161, v161
	v_exp_f32_e32 v165, v165
	v_exp_f32_e32 v154, v154
	v_exp_f32_e32 v158, v158
	v_exp_f32_e32 v162, v162
	v_exp_f32_e32 v166, v166
	v_exp_f32_e32 v155, v155
	v_exp_f32_e32 v159, v159
	v_exp_f32_e32 v163, v163
	v_exp_f32_e32 v167, v167
	v_add_f32_e32 v152, 1.0, v152
	v_add_f32_e32 v156, 1.0, v156
	v_add_f32_e32 v160, 1.0, v160
	v_add_f32_e32 v164, 1.0, v164
	v_add_f32_e32 v153, 1.0, v153
	v_add_f32_e32 v157, 1.0, v157
	v_add_f32_e32 v161, 1.0, v161
	v_add_f32_e32 v165, 1.0, v165
	v_add_f32_e32 v154, 1.0, v154
	v_add_f32_e32 v158, 1.0, v158
	v_add_f32_e32 v162, 1.0, v162
	v_add_f32_e32 v166, 1.0, v166
	v_add_f32_e32 v155, 1.0, v155
	v_add_f32_e32 v159, 1.0, v159
	v_add_f32_e32 v163, 1.0, v163
	v_add_f32_e32 v167, 1.0, v167
	v_log_f32_e32 v152, v152
	v_log_f32_e32 v156, v156
	v_log_f32_e32 v160, v160
	v_log_f32_e32 v164, v164
	v_log_f32_e32 v153, v153
	v_log_f32_e32 v157, v157
	v_log_f32_e32 v161, v161
	v_log_f32_e32 v165, v165
	v_log_f32_e32 v154, v154
	v_log_f32_e32 v158, v158
	v_log_f32_e32 v162, v162
	v_log_f32_e32 v166, v166
	v_log_f32_e32 v155, v155
	v_log_f32_e32 v159, v159
	v_log_f32_e32 v163, v163
	v_log_f32_e32 v167, v167
	v_mul_f32_e32 v69, 0x3f317217, v152
	v_mul_f32_e32 v70, 0x3f317217, v156
	v_mul_f32_e32 v71, 0x3f317217, v160
	v_mul_f32_e32 v72, 0x3f317217, v164
	v_mul_f32_e32 v73, 0x3f317217, v153
	v_mul_f32_e32 v74, 0x3f317217, v157
	v_mul_f32_e32 v75, 0x3f317217, v161
	v_mul_f32_e32 v76, 0x3f317217, v165
	v_mul_f32_e32 v77, 0x3f317217, v154
	v_mul_f32_e32 v78, 0x3f317217, v158
	v_mul_f32_e32 v79, 0x3f317217, v162
	v_mul_f32_e32 v80, 0x3f317217, v166
	v_mul_f32_e32 v81, 0x3f317217, v155
	v_mul_f32_e32 v82, 0x3f317217, v159
	v_mul_f32_e32 v83, 0x3f317217, v163
	v_mul_f32_e32 v84, 0x3f317217, v167
	v_fma_f32 v69, v152, s15, -v69
	v_fma_f32 v70, v156, s15, -v70
	v_fma_f32 v71, v160, s15, -v71
	v_fma_f32 v72, v164, s15, -v72
	v_fma_f32 v73, v153, s15, -v73
	v_fma_f32 v74, v157, s15, -v74
	v_fma_f32 v75, v161, s15, -v75
	v_fma_f32 v76, v165, s15, -v76
	v_fma_f32 v77, v154, s15, -v77
	v_fma_f32 v78, v158, s15, -v78
	v_fma_f32 v79, v162, s15, -v79
	v_fma_f32 v80, v166, s15, -v80
	v_fma_f32 v81, v155, s15, -v81
	v_fma_f32 v82, v159, s15, -v82
	v_fma_f32 v83, v163, s15, -v83
	v_fma_f32 v84, v167, s15, -v84
	v_fmac_f32_e32 v69, 0x3377d1cf, v152
	v_fmac_f32_e32 v70, 0x3377d1cf, v156
	v_fmac_f32_e32 v71, 0x3377d1cf, v160
	v_fmac_f32_e32 v72, 0x3377d1cf, v164
	v_fmac_f32_e32 v73, 0x3377d1cf, v153
	v_fmac_f32_e32 v74, 0x3377d1cf, v157
	v_fmac_f32_e32 v75, 0x3377d1cf, v161
	v_fmac_f32_e32 v76, 0x3377d1cf, v165
	v_fmac_f32_e32 v77, 0x3377d1cf, v154
	v_fmac_f32_e32 v78, 0x3377d1cf, v158
	v_fmac_f32_e32 v79, 0x3377d1cf, v162
	v_fmac_f32_e32 v80, 0x3377d1cf, v166
	v_fmac_f32_e32 v81, 0x3377d1cf, v155
	v_fmac_f32_e32 v82, 0x3377d1cf, v159
	v_fmac_f32_e32 v83, 0x3377d1cf, v163
	v_fmac_f32_e32 v84, 0x3377d1cf, v167
	v_fmac_f32_e32 v69, 0x3f317217, v152
	v_fmac_f32_e32 v70, 0x3f317217, v156
	v_fmac_f32_e32 v71, 0x3f317217, v160
	v_fmac_f32_e32 v72, 0x3f317217, v164
	v_fmac_f32_e32 v73, 0x3f317217, v153
	v_fmac_f32_e32 v74, 0x3f317217, v157
	v_fmac_f32_e32 v75, 0x3f317217, v161
	v_fmac_f32_e32 v76, 0x3f317217, v165
	v_fmac_f32_e32 v77, 0x3f317217, v154
	v_fmac_f32_e32 v78, 0x3f317217, v158
	v_fmac_f32_e32 v79, 0x3f317217, v162
	v_fmac_f32_e32 v80, 0x3f317217, v166
	v_fmac_f32_e32 v81, 0x3f317217, v155
	v_fmac_f32_e32 v82, 0x3f317217, v159
	v_fmac_f32_e32 v83, 0x3f317217, v163
	v_fmac_f32_e32 v84, 0x3f317217, v167
	v_sub_f32_e32 v152, v53, v69
	v_sub_f32_e32 v156, v54, v70
	v_sub_f32_e32 v160, v55, v71
	v_sub_f32_e32 v164, v56, v72
	v_sub_f32_e32 v153, v57, v73
	v_sub_f32_e32 v157, v58, v74
	v_sub_f32_e32 v161, v59, v75
	v_sub_f32_e32 v165, v60, v76
	v_sub_f32_e32 v154, v61, v77
	v_sub_f32_e32 v158, v62, v78
	v_sub_f32_e32 v162, v63, v79
	v_sub_f32_e32 v166, v64, v80
	v_sub_f32_e32 v155, v65, v81
	v_sub_f32_e32 v159, v66, v82
	v_sub_f32_e32 v163, v67, v83
	v_sub_f32_e32 v167, v68, v84
	v_fma_mixlo_f16 v86, v152, s17, 0
	v_fma_mixlo_f16 v87, v160, s17, 0
	v_fma_mixlo_f16 v88, v153, s17, 0
	v_fma_mixlo_f16 v89, v161, s17, 0
	v_fma_mixlo_f16 v90, v154, s17, 0
	v_fma_mixlo_f16 v91, v162, s17, 0
	v_fma_mixlo_f16 v92, v155, s17, 0
	v_fma_mixlo_f16 v93, v163, s17, 0
	v_fma_mixhi_f16 v86, v156, s17, 0
	v_fma_mixhi_f16 v87, v164, s17, 0
	v_fma_mixhi_f16 v88, v157, s17, 0
	v_fma_mixhi_f16 v89, v165, s17, 0
	v_fma_mixhi_f16 v90, v158, s17, 0
	v_fma_mixhi_f16 v91, v166, s17, 0
	v_fma_mixhi_f16 v92, v159, s17, 0
	v_fma_mixhi_f16 v93, v167, s17, 0
	global_store_dwordx2 v[172:173], v[86:87], off
	global_store_dwordx2 v[172:173], v[88:89], off offset:1024
	global_store_dwordx2 v[172:173], v[90:91], off offset:2048
	global_store_dwordx2 v[172:173], v[92:93], off offset:3072
	s_add_i32 s19, s19, s26
	s_add_i32 s10, s10, s34
	s_cmpk_gt_i32 s19, 0xff
	s_barrier
	s_cbranch_scc0 .LBB0_225
